# diff attention loop: K/V tile prefetch two tiles ahead (second staging register set v224-239)
# speedup vs baseline: 1.0045x; 1.0044x over previous
.LBB0_472:
	s_or_b64 exec, exec, s[0:1]
	s_waitcnt vmcnt(5)
	v_lshlrev_b32_e32 v35, 16, v30
	v_and_b32_e32 v30, 0xffff0000, v30
	v_mul_f32_e32 v30, 0x3e38aa3b, v30
	v_mul_f32_e32 v35, 0x3e38aa3b, v35
	v_cvt_pk_bf16_f32 v98, v35, v30
	v_lshlrev_b32_e32 v30, 16, v31
	v_mul_f32_e32 v30, 0x3e38aa3b, v30
	v_and_b32_e32 v31, 0xffff0000, v31
	v_mul_f32_e32 v31, 0x3e38aa3b, v31
	v_cvt_pk_bf16_f32 v99, v30, v31
	v_lshlrev_b32_e32 v30, 16, v32
	v_mul_f32_e32 v30, 0x3e38aa3b, v30
	v_and_b32_e32 v31, 0xffff0000, v32
	v_mul_f32_e32 v31, 0x3e38aa3b, v31
	v_cvt_pk_bf16_f32 v100, v30, v31
	v_lshlrev_b32_e32 v30, 16, v33
	v_mul_f32_e32 v30, 0x3e38aa3b, v30
	v_and_b32_e32 v31, 0xffff0000, v33
	v_mul_f32_e32 v31, 0x3e38aa3b, v31
	v_cvt_pk_bf16_f32 v101, v30, v31
	s_waitcnt vmcnt(3)
	v_lshlrev_b32_e32 v30, 16, v26
	v_and_b32_e32 v26, 0xffff0000, v26
	v_mul_f32_e32 v26, 0x3e38aa3b, v26
	v_mul_f32_e32 v30, 0x3e38aa3b, v30
	v_cvt_pk_bf16_f32 v102, v30, v26
	v_lshlrev_b32_e32 v26, 16, v27
	v_mul_f32_e32 v26, 0x3e38aa3b, v26
	v_and_b32_e32 v27, 0xffff0000, v27
	v_mul_f32_e32 v27, 0x3e38aa3b, v27
	v_cvt_pk_bf16_f32 v103, v26, v27
	v_lshlrev_b32_e32 v26, 16, v28
	v_mul_f32_e32 v26, 0x3e38aa3b, v26
	v_and_b32_e32 v27, 0xffff0000, v28
	v_mul_f32_e32 v27, 0x3e38aa3b, v27
	v_cvt_pk_bf16_f32 v104, v26, v27
	v_lshlrev_b32_e32 v26, 16, v29
	v_mul_f32_e32 v26, 0x3e38aa3b, v26
	v_and_b32_e32 v27, 0xffff0000, v29
	v_mul_f32_e32 v27, 0x3e38aa3b, v27
	v_cvt_pk_bf16_f32 v105, v26, v27
	v_lshlrev_b32_e32 v26, 16, v22
	v_and_b32_e32 v22, 0xffff0000, v22
	v_mul_f32_e32 v22, 0x3e38aa3b, v22
	v_mul_f32_e32 v26, 0x3e38aa3b, v26
	v_cvt_pk_bf16_f32 v106, v26, v22
	v_lshlrev_b32_e32 v22, 16, v23
	v_mul_f32_e32 v22, 0x3e38aa3b, v22
	v_and_b32_e32 v23, 0xffff0000, v23
	v_mul_f32_e32 v23, 0x3e38aa3b, v23
	v_cvt_pk_bf16_f32 v107, v22, v23
	v_lshlrev_b32_e32 v22, 16, v24
	v_mul_f32_e32 v22, 0x3e38aa3b, v22
	v_and_b32_e32 v23, 0xffff0000, v24
	v_mul_f32_e32 v23, 0x3e38aa3b, v23
	v_cvt_pk_bf16_f32 v108, v22, v23
	v_lshlrev_b32_e32 v22, 16, v25
	v_mul_f32_e32 v22, 0x3e38aa3b, v22
	v_and_b32_e32 v23, 0xffff0000, v25
	v_mul_f32_e32 v23, 0x3e38aa3b, v23
	v_cvt_pk_bf16_f32 v109, v22, v23
	v_lshlrev_b32_e32 v22, 16, v14
	v_and_b32_e32 v14, 0xffff0000, v14
	v_mul_f32_e32 v14, 0x3e38aa3b, v14
	v_mul_f32_e32 v22, 0x3e38aa3b, v22
	v_cvt_pk_bf16_f32 v110, v22, v14
	v_lshlrev_b32_e32 v14, 16, v15
	v_mul_f32_e32 v14, 0x3e38aa3b, v14
	v_and_b32_e32 v15, 0xffff0000, v15
	v_mul_f32_e32 v15, 0x3e38aa3b, v15
	v_cvt_pk_bf16_f32 v111, v14, v15
	v_lshlrev_b32_e32 v14, 16, v16
	v_mul_f32_e32 v14, 0x3e38aa3b, v14
	v_and_b32_e32 v15, 0xffff0000, v16
	v_mul_f32_e32 v15, 0x3e38aa3b, v15
	v_cvt_pk_bf16_f32 v112, v14, v15
	v_lshlrev_b32_e32 v14, 16, v17
	v_mul_f32_e32 v14, 0x3e38aa3b, v14
	v_and_b32_e32 v15, 0xffff0000, v17
	s_movk_i32 s0, 0x110
	v_mul_f32_e32 v15, 0x3e38aa3b, v15
	v_cvt_pk_bf16_f32 v113, v14, v15
	v_mul_lo_u32 v14, v37, s0
	v_lshl_add_u32 v151, v38, 4, v14
	s_movk_i32 s0, 0x90
	v_mul_lo_u32 v14, v36, s0
	v_lshlrev_b32_e32 v16, 3, v134
	v_add_u32_e32 v17, 0, v151
	v_and_b32_e32 v15, 0x60, v34
	ds_write_b128 v17, v[6:9]
	s_waitcnt vmcnt(1)
	ds_write_b128 v17, v[18:21] offset:8704
	v_and_or_b32 v6, v16, 8, v14
	v_add_u32_e32 v152, v6, v15
	v_add_u32_e32 v6, 0, v152
	v_add_u32_e32 v7, 0x4000, v6
	ds_write2_b64 v7, v[2:3], v[4:5] offset0:128 offset1:130
	v_add_u32_e32 v2, 0x6800, v6
	v_readlane_b32 s0, v253, 49
	s_waitcnt vmcnt(0)
	ds_write2_b64 v2, v[10:11], v[12:13] offset1:2
	s_waitcnt lgkmcnt(0)
	v_mov_b32_e32 v2, s0
	s_barrier
	ds_read_b32 v149, v2
	v_mov_b32_e32 v137, 1.0
	v_mov_b32_e32 v17, 0
	s_cmp_lt_i32 s2, 0
	v_mov_b32_e32 v16, 0
	v_mov_b32_e32 v15, 0
	v_mov_b32_e32 v14, 0
	v_mov_b32_e32 v13, 0
	v_mov_b32_e32 v12, 0
	v_mov_b32_e32 v11, 0
	v_mov_b32_e32 v10, 0
	v_mov_b32_e32 v9, 0
	v_mov_b32_e32 v8, 0
	v_mov_b32_e32 v7, 0
	v_mov_b32_e32 v6, 0
	v_mov_b32_e32 v5, 0
	v_mov_b32_e32 v4, 0
	v_mov_b32_e32 v3, 0
	v_mov_b32_e32 v2, 0
	v_mov_b32_e32 v33, 0
	v_mov_b32_e32 v32, 0
	v_mov_b32_e32 v31, 0
	v_mov_b32_e32 v30, 0
	v_mov_b32_e32 v29, 0
	v_mov_b32_e32 v28, 0
	v_mov_b32_e32 v27, 0
	v_mov_b32_e32 v26, 0
	v_mov_b32_e32 v25, 0
	v_mov_b32_e32 v24, 0
	v_mov_b32_e32 v23, 0
	v_mov_b32_e32 v22, 0
	v_mov_b32_e32 v21, 0
	v_mov_b32_e32 v20, 0
	v_mov_b32_e32 v19, 0
	v_mov_b32_e32 v18, 0
	v_mov_b32_e32 v49, 0
	v_mov_b32_e32 v48, 0
	v_mov_b32_e32 v47, 0
	v_mov_b32_e32 v46, 0
	v_mov_b32_e32 v45, 0
	v_mov_b32_e32 v44, 0
	v_mov_b32_e32 v43, 0
	v_mov_b32_e32 v42, 0
	v_mov_b32_e32 v41, 0
	v_mov_b32_e32 v40, 0
	v_mov_b32_e32 v39, 0
	v_mov_b32_e32 v38, 0
	v_mov_b32_e32 v37, 0
	v_mov_b32_e32 v36, 0
	v_mov_b32_e32 v35, 0
	v_mov_b32_e32 v34, 0
	v_mov_b32_e32 v65, 0
	v_mov_b32_e32 v64, 0
	v_mov_b32_e32 v63, 0
	v_mov_b32_e32 v62, 0
	v_mov_b32_e32 v61, 0
	v_mov_b32_e32 v60, 0
	v_mov_b32_e32 v59, 0
	v_mov_b32_e32 v58, 0
	v_mov_b32_e32 v57, 0
	v_mov_b32_e32 v56, 0
	v_mov_b32_e32 v55, 0
	v_mov_b32_e32 v54, 0
	v_mov_b32_e32 v53, 0
	v_mov_b32_e32 v52, 0
	v_mov_b32_e32 v51, 0
	v_mov_b32_e32 v50, 0
	v_mov_b32_e32 v131, 0
	s_cbranch_scc1 .LBB0_492
	s_movk_i32 s0, 0x1c00
	v_mad_i64_i32 v[2:3], s[0:1], v70, s0, 0
	v_lshl_add_u64 v[2:3], v[2:3], 0, v[0:1]
	v_mov_b32_e32 v14, v1
	v_mov_b32_e32 v15, v1
	s_mov_b64 s[0:1], 0x1800
	v_lshl_add_u64 v[144:145], s[42:43], 0, v[2:3]
	v_mov_b32_e32 v0, v1
	v_mov_b32_e32 v2, v1
	v_mov_b32_e32 v3, v1
	v_mov_b32_e32 v4, v1
	v_mov_b32_e32 v5, v1
	v_mov_b32_e32 v6, v1
	v_mov_b32_e32 v7, v1
	v_mov_b32_e32 v8, v1
	v_mov_b32_e32 v9, v1
	v_mov_b32_e32 v10, v1
	v_mov_b32_e32 v11, v1
	v_mov_b32_e32 v12, v1
	v_mov_b32_e32 v13, v1
	v_mov_b64_e32 v[64:65], v[14:15]
	v_mov_b64_e32 v[48:49], v[14:15]
	v_mov_b64_e32 v[32:33], v[14:15]
	v_lshl_add_u64 v[140:141], v[66:67], 0, s[0:1]
	s_mov_b64 s[0:1], 0x200000
	s_lshl_b32 s2, s2, 1
	v_ashrrev_i32_e32 v155, 8, v134
	v_subrev_u32_e32 v156, 63, v69
	v_mov_b64_e32 v[62:63], v[12:13]
	v_mov_b64_e32 v[60:61], v[10:11]
	v_mov_b64_e32 v[58:59], v[8:9]
	v_mov_b64_e32 v[56:57], v[6:7]
	v_mov_b64_e32 v[54:55], v[4:5]
	v_mov_b64_e32 v[52:53], v[2:3]
	v_mov_b64_e32 v[50:51], v[0:1]
	v_mov_b64_e32 v[46:47], v[12:13]
	v_mov_b64_e32 v[44:45], v[10:11]
	v_mov_b64_e32 v[42:43], v[8:9]
	v_mov_b64_e32 v[40:41], v[6:7]
	v_mov_b64_e32 v[38:39], v[4:5]
	v_mov_b64_e32 v[36:37], v[2:3]
	v_mov_b64_e32 v[34:35], v[0:1]
	v_mov_b64_e32 v[30:31], v[12:13]
	v_mov_b64_e32 v[28:29], v[10:11]
	v_mov_b64_e32 v[26:27], v[8:9]
	v_mov_b64_e32 v[24:25], v[6:7]
	v_mov_b64_e32 v[22:23], v[4:5]
	v_mov_b64_e32 v[20:21], v[2:3]
	v_mov_b64_e32 v[18:19], v[0:1]
	v_mov_b64_e32 v[16:17], v[14:15]
	v_lshl_add_u64 v[142:143], v[138:139], 0, s[0:1]
	v_add_u32_e32 v157, s2, v155
	v_mul_u32_u24_e32 v154, 0x110, v68
	v_mul_i32_i24_e32 v153, -4, v135
	v_mul_u32_u24_e32 v133, 0x90, v68
	v_mad_i32_i24 v158, v135, -4, v68
	s_or_b32 s3, s2, 1
	s_mov_b32 s4, 0
	v_mov_b32_e32 v150, 0xff800000
	v_mov_b32_e32 v131, 0
	s_mov_b32 s52, 64
	v_mov_b32_e32 v159, v156
	v_mov_b64_e32 v[14:15], v[12:13]
	v_mov_b64_e32 v[12:13], v[10:11]
	v_mov_b64_e32 v[10:11], v[8:9]
	v_mov_b64_e32 v[8:9], v[6:7]
	v_mov_b64_e32 v[6:7], v[4:5]
	v_mov_b64_e32 v[4:5], v[2:3]
	v_mov_b64_e32 v[2:3], v[0:1]
	s_add_i32 s0, s52, 32
	v_mov_b32_e32 v0, 0x1c00
	v_mad_u64_u32 v[240:241], s[0:1], s0, v0, v[140:141]
	s_lshl_b64 s[0:1], s[52:53], 1
	v_lshl_add_u64 v[242:243], v[138:139], 0, s[0:1]
	v_lshl_add_u64 v[244:245], v[142:143], 0, s[0:1]
	global_load_dwordx4 v[224:227], v[144:145], off
	global_load_dwordx4 v[228:231], v[240:241], off
	global_load_dwordx4 v[232:235], v[242:243], off
	global_load_dwordx4 v[236:239], v[244:245], off
	s_add_i32 s52, s52, 64
	s_mov_b64 s[0:1], 0x70000
	v_lshl_add_u64 v[144:145], v[144:145], 0, s[0:1]
	s_branch .LBB0_475

.LBB0_475:
	s_cmp_le_i32 s4, s2
	s_cselect_b64 s[62:63], -1, 0
	s_cmp_ge_i32 s4, s2
	s_cbranch_scc1 .LBB0_478
	s_mov_b64 s[12:13], s[52:53]
	s_add_i32 s0, s12, 32
	v_mov_b32_e32 v0, 0x1c00
	v_mad_u64_u32 v[66:67], s[0:1], s0, v0, v[140:141]
	s_lshl_b64 s[0:1], s[52:53], 1
	v_lshl_add_u64 v[68:69], v[138:139], 0, s[0:1]
	v_lshl_add_u64 v[240:241], v[142:143], 0, s[0:1]
	s_bitcmp1_b32 s4, 0
	s_cbranch_scc1 .Ldf_ld_odd
	global_load_dwordx4 v[114:117], v[144:145], off
	global_load_dwordx4 v[118:121], v[66:67], off
	global_load_dwordx4 v[122:125], v[68:69], off
	global_load_dwordx4 v[126:129], v[240:241], off
	s_branch .Ldf_ld_done
.Ldf_ld_odd:
	global_load_dwordx4 v[224:227], v[144:145], off
	global_load_dwordx4 v[228:231], v[66:67], off
	global_load_dwordx4 v[232:235], v[68:69], off
	global_load_dwordx4 v[236:239], v[240:241], off
.Ldf_ld_done:
	v_cmp_le_i32_e32 vcc, s4, v157
	s_and_saveexec_b64 s[64:65], vcc
	s_cbranch_execnz .LBB0_479

.LBB0_484:
	s_andn2_b32 s0, 1, s4
	s_mul_i32 s0, s0, 0x8c00
	s_add_i32 s0, s0, 0
	v_add_u32_e32 v0, s0, v151
	v_add_u32_e32 v242, s0, v152
	v_add_u32_e32 v243, 0x4000, v242
	v_add_u32_e32 v242, 0x6800, v242
	s_cmp_lt_i32 s4, s2
	s_cbranch_scc1 .Ldf_w4
	s_waitcnt vmcnt(0)
	s_branch .Ldf_wd

.Ldf_wd:
	s_bitcmp1_b32 s4, 0
	s_cbranch_scc1 .Ldf_st_odd
	ds_write_b128 v0, v[224:227]
	ds_write_b128 v0, v[228:231] offset:8704
	ds_write2_b64 v243, v[232:233], v[234:235] offset0:128 offset1:130
	ds_write2_b64 v242, v[236:237], v[238:239] offset1:2
	s_branch .LBB0_474
.Ldf_st_odd:
	ds_write_b128 v0, v[114:117]
	ds_write_b128 v0, v[118:121] offset:8704
	ds_write2_b64 v243, v[122:123], v[124:125] offset0:128 offset1:130
	ds_write2_b64 v242, v[126:127], v[128:129] offset1:2
	s_branch .LBB0_474
